# g2 staging with 8 loads in flight; dead denormal-rescale code around v_log removed in the GLA and RWKV decay computations (bit-exact)
# speedup vs baseline: 1.0190x; 1.0116x over previous
; __device__ __forceinline__ void st_bf(LAS bf16_t* p, float x) { *p = (bf16_t)(cvt_pk_bf16(x, x) & 0xffffu); }
; __device__ void rwkv_post_phase(const Params& p, int l, LAS unsigned char* lds) {
;     ...
;     for (int idx = tid; idx < 96 * 512; idx += 512) { const int i = idx >> 9, c = idx & 511; st_bf(g2T + c * 104 + i, g2[idx]); }
.LBB0_190:
	v_ashrrev_i32_e32 v9, 31, v2
	v_mov_b32_e32 v8, v2
	v_lshl_add_u64 v[8:9], v[8:9], 2, s[22:23]
	v_add_co_u32_e32 v10, vcc, 0x1000, v8
	s_nop 1
	v_addc_co_u32_e32 v11, vcc, 0, v9, vcc
	v_add_co_u32_e32 v12, vcc, 0x3000, v8
	s_nop 1
	v_addc_co_u32_e32 v13, vcc, 0, v9, vcc
	global_load_dword v24, v[10:11], off offset:-4096
	global_load_dword v25, v[10:11], off offset:-2048
	global_load_dword v26, v[10:11], off
	global_load_dword v27, v[10:11], off offset:2048
	global_load_dword v28, v[12:13], off offset:-4096
	global_load_dword v29, v[12:13], off offset:-2048
	global_load_dword v30, v[12:13], off
	global_load_dword v31, v[12:13], off offset:2048
	v_ashrrev_i32_e32 v7, 9, v2
	v_lshl_add_u32 v7, v7, 1, v0
	v_add_u32_e32 v6, -4, v6
	v_cmp_eq_u32_e32 vcc, 0, v6
	s_or_b64 s[34:35], vcc, s[34:35]
	v_add_u32_e32 v2, 0x1000, v2
	v_add_u32_e32 v3, 0x1000, v3
	s_waitcnt vmcnt(0)
	v_cvt_pk_bf16_f32 v8, v24, v25
	v_cvt_pk_bf16_f32 v9, v26, v27
	v_cvt_pk_bf16_f32 v10, v28, v29
	v_cvt_pk_bf16_f32 v11, v30, v31
	ds_write_b16 v7, v8
	ds_write_b16_d16_hi v7, v8 offset:2
	ds_write_b16 v7, v9 offset:4
	ds_write_b16_d16_hi v7, v9 offset:6
	ds_write_b16 v7, v10 offset:8
	ds_write_b16_d16_hi v7, v10 offset:10
	ds_write_b16 v7, v11 offset:12
	ds_write_b16_d16_hi v7, v11 offset:14
	s_andn2_b64 exec, exec, s[34:35]
	s_cbranch_execnz .LBB0_190
	s_or_b64 exec, exec, s[34:35]

; #define LAS __attribute__((address_space(3)))
; __device__ __forceinline__ unsigned cvt_pk_bf16(float lo, float hi) { const f32x2_t v = {lo, hi}; const bf16x2_t b = __builtin_convertvector(v, bf16x2_t); return __builtin_bit_cast(unsigned, b); }
; __device__ __forceinline__ float tanh_(float x) { const float t = __expf(-2.0f * fabsf(x)); const float r = (1.0f - t) * __builtin_amdgcn_rcpf(1.0f + t); return x < 0.f ? -r : r; }
; #define LBAR() do { asm volatile("s_waitcnt lgkmcnt(0)" ::: "memory"); __builtin_amdgcn_s_barrier(); asm volatile("" ::: "memory"); } while (0)
; __device__ void rwkv_chunk_phase(const Params& p, int l, LAS unsigned char* lds) {
;     ...
;             for (int hf = 0; hf < 2; ++hf) { float fc[8], fp[8], fn[8]; unpack8(rc[hf], fc); unpack8(rp[hf], fp); unpack8(rn[hf], fn);
;                 const f32x4 m0 = *(const LAS f32x4*)(mu_s + cg * 16 + hf * 8), m1 = *(const LAS f32x4*)(mu_s + cg * 16 + hf * 8 + 4);
;                 f32x4 x0, x1;
; #pragma unroll
;                 for (int j = 0; j < 4; ++j) { x0[j] = fc[j] + m0[j] * (0.5f * (fp[j] + fn[j]) - fc[j]); x1[j] = fc[4 + j] + m1[j] * (0.5f * (fp[4 + j] + fn[4 + j]) - fc[4 + j]); }
;                 *(LAS f32x4*)(sh_s + tok * 256 + cg * 16 + hf * 8) = x0; *(LAS f32x4*)(sh_s + tok * 256 + cg * 16 + hf * 8 + 4) = x1; }
;             LBAR();
;             {   const int rt = wid >> 2, ct = wid & 3, row = rt * 16 + r16;
;                 const f32x4 d0 = *(const LAS f32x4*)(sh_s + row * 256 + 192 + quad * 8), d1 = *(const LAS f32x4*)(sh_s + row * 256 + 196 + quad * 8);
;                 const f32x4 e0 = *(const LAS f32x4*)(sh_s + row * 256 + 224 + quad * 8), e1 = *(const LAS f32x4*)(sh_s + row * 256 + 228 + quad * 8);
;                 u32x4 aw, aa;
;                 aw.x = cvt_pk_bf16(tanh_(d0[0]), tanh_(d0[1])); aw.y = cvt_pk_bf16(tanh_(d0[2]), tanh_(d0[3])); aw.z = cvt_pk_bf16(tanh_(d1[0]), tanh_(d1[1])); aw.w = cvt_pk_bf16(tanh_(d1[2]), tanh_(d1[3]));
;                 aa.x = cvt_pk_bf16(e0[0], e0[1]); aa.y = cvt_pk_bf16(e0[2], e0[3]); aa.z = cvt_pk_bf16(e1[0], e1[1]); aa.w = cvt_pk_bf16(e1[2], e1[3]);
;                 const bf16x8 bw = *(const LAS bf16x8*)(w2T + (ct * 16 + r16) * 40 + quad * 8), ba = *(const LAS bf16x8*)(a2T + (ct * 16 + r16) * 40 + quad * 8);
.Lrw_top:
	ds_read_b128 v[32:35], v206 offset:17664
	ds_read_b128 v[36:39], v206 offset:17680
	s_waitcnt vmcnt(1) lgkmcnt(0)
	v_lshlrev_b32_e32 v40, 16, v16
	v_and_b32_e32 v41, 0xffff0000, v16
	v_lshlrev_b32_e32 v42, 16, v24
	v_and_b32_e32 v43, 0xffff0000, v24
	v_lshlrev_b32_e32 v2, 16, v8
	v_and_b32_e32 v3, 0xffff0000, v8
	v_pk_add_f32 v[40:41], v[40:41], v[42:43]
	v_lshlrev_b32_e32 v42, 16, v26
	v_pk_fma_f32 v[40:41], v[40:41], 0.5, v[2:3] op_sel_hi:[1,0,1] neg_lo:[0,0,1] neg_hi:[0,0,1]
	v_and_b32_e32 v43, 0xffff0000, v26
	v_pk_fma_f32 v[32:33], v[40:41], v[32:33], v[2:3]
	v_lshlrev_b32_e32 v40, 16, v18
	v_and_b32_e32 v41, 0xffff0000, v18
	v_lshlrev_b32_e32 v2, 16, v10
	v_and_b32_e32 v3, 0xffff0000, v10
	v_pk_add_f32 v[40:41], v[40:41], v[42:43]
	v_lshlrev_b32_e32 v42, 16, v25
	v_pk_fma_f32 v[40:41], v[40:41], 0.5, v[2:3] op_sel_hi:[1,0,1] neg_lo:[0,0,1] neg_hi:[0,0,1]
	v_and_b32_e32 v43, 0xffff0000, v25
	v_pk_fma_f32 v[36:37], v[40:41], v[36:37], v[2:3]
	v_lshlrev_b32_e32 v40, 16, v17
	v_and_b32_e32 v41, 0xffff0000, v17
	v_lshlrev_b32_e32 v2, 16, v9
	v_and_b32_e32 v3, 0xffff0000, v9
	v_pk_add_f32 v[40:41], v[40:41], v[42:43]
	v_lshlrev_b32_e32 v42, 16, v27
	v_pk_fma_f32 v[40:41], v[40:41], 0.5, v[2:3] op_sel_hi:[1,0,1] neg_lo:[0,0,1] neg_hi:[0,0,1]
	v_and_b32_e32 v43, 0xffff0000, v27
	v_pk_fma_f32 v[34:35], v[40:41], v[34:35], v[2:3]
	v_lshlrev_b32_e32 v40, 16, v19
	v_and_b32_e32 v41, 0xffff0000, v19
	v_lshlrev_b32_e32 v2, 16, v11
	v_and_b32_e32 v3, 0xffff0000, v11
	v_pk_add_f32 v[40:41], v[40:41], v[42:43]
	v_lshlrev_b32_e32 v42, 16, v28
	v_pk_fma_f32 v[40:41], v[40:41], 0.5, v[2:3] op_sel_hi:[1,0,1] neg_lo:[0,0,1] neg_hi:[0,0,1]
	v_and_b32_e32 v43, 0xffff0000, v28
	v_pk_fma_f32 v[38:39], v[40:41], v[38:39], v[2:3]
	ds_write_b128 v87, v[32:35]
	ds_write_b128 v87, v[36:39] offset:16
	ds_read_b128 v[32:35], v206 offset:17696
	ds_read_b128 v[36:39], v206 offset:17712
	v_lshlrev_b32_e32 v40, 16, v20
	v_and_b32_e32 v41, 0xffff0000, v20
	v_lshlrev_b32_e32 v2, 16, v12
	v_and_b32_e32 v3, 0xffff0000, v12
	v_pk_add_f32 v[40:41], v[40:41], v[42:43]
	v_lshlrev_b32_e32 v42, 16, v30
	v_pk_fma_f32 v[40:41], v[40:41], 0.5, v[2:3] op_sel_hi:[1,0,1] neg_lo:[0,0,1] neg_hi:[0,0,1]
	v_and_b32_e32 v43, 0xffff0000, v30
	s_waitcnt lgkmcnt(1)
	v_pk_fma_f32 v[32:33], v[40:41], v[32:33], v[2:3]
	v_lshlrev_b32_e32 v40, 16, v22
	v_and_b32_e32 v41, 0xffff0000, v22
	v_lshlrev_b32_e32 v2, 16, v14
	v_and_b32_e32 v3, 0xffff0000, v14
	v_pk_add_f32 v[40:41], v[40:41], v[42:43]
	v_lshlrev_b32_e32 v42, 16, v29
	v_pk_fma_f32 v[40:41], v[40:41], 0.5, v[2:3] op_sel_hi:[1,0,1] neg_lo:[0,0,1] neg_hi:[0,0,1]
	v_and_b32_e32 v43, 0xffff0000, v29
	s_waitcnt lgkmcnt(0)
	v_pk_fma_f32 v[36:37], v[40:41], v[36:37], v[2:3]
	v_lshlrev_b32_e32 v40, 16, v21
	v_and_b32_e32 v41, 0xffff0000, v21
	v_lshlrev_b32_e32 v2, 16, v13
	v_and_b32_e32 v3, 0xffff0000, v13
	v_pk_add_f32 v[40:41], v[40:41], v[42:43]
	v_lshlrev_b32_e32 v42, 16, v31
	v_pk_fma_f32 v[40:41], v[40:41], 0.5, v[2:3] op_sel_hi:[1,0,1] neg_lo:[0,0,1] neg_hi:[0,0,1]
	v_and_b32_e32 v43, 0xffff0000, v31
	v_pk_fma_f32 v[34:35], v[40:41], v[34:35], v[2:3]
	v_lshlrev_b32_e32 v40, 16, v23
	v_and_b32_e32 v41, 0xffff0000, v23
	v_lshlrev_b32_e32 v2, 16, v15
	v_and_b32_e32 v3, 0xffff0000, v15
	v_pk_add_f32 v[40:41], v[40:41], v[42:43]
	s_add_i32 s62, s65, 1
	v_pk_fma_f32 v[40:41], v[40:41], 0.5, v[2:3] op_sel_hi:[1,0,1] neg_lo:[0,0,1] neg_hi:[0,0,1]
	s_nop 0
	v_pk_fma_f32 v[38:39], v[40:41], v[38:39], v[2:3]
	ds_write_b128 v87, v[32:35] offset:32
	ds_write_b128 v87, v[36:39] offset:48
	s_waitcnt lgkmcnt(0)
	s_barrier
	ds_read_b128 v[32:35], v89 offset:768
	ds_read_b128 v[36:39], v89 offset:784
	ds_read_b128 v[40:43], v89 offset:896
	s_waitcnt lgkmcnt(2)
	v_mul_f32_e64 v0, |v32|, -2.0
	v_mul_f32_e32 v0, 0x3fb8aa3b, v0
	v_exp_f32_e32 v2, v0
	v_mul_f32_e64 v0, |v33|, -2.0
	v_mul_f32_e32 v0, 0x3fb8aa3b, v0
	v_exp_f32_e32 v3, v0
	v_add_f32_e32 v0, 1.0, v2
	v_rcp_f32_e32 v44, v0
	v_cmp_gt_f32_e32 vcc, 0, v33
	v_add_f32_e32 v0, 1.0, v3
	v_rcp_f32_e32 v45, v0
	v_mul_f32_e64 v0, |v34|, -2.0
	v_pk_add_f32 v[2:3], v[2:3], 1.0 op_sel_hi:[1,0] neg_lo:[1,0] neg_hi:[1,0]
	v_mul_f32_e32 v0, 0x3fb8aa3b, v0
	v_pk_mul_f32 v[2:3], v[2:3], v[44:45]
	v_exp_f32_e32 v44, v0
	v_mul_f32_e64 v0, |v35|, -2.0
	v_mul_f32_e32 v0, 0x3fb8aa3b, v0
	v_exp_f32_e32 v45, v0
	v_cndmask_b32_e64 v0, v3, -v3, vcc
	v_add_f32_e32 v3, 1.0, v44
	v_cmp_gt_f32_e32 vcc, 0, v32
	v_rcp_f32_e32 v46, v3
	v_add_f32_e32 v3, 1.0, v45
	v_cndmask_b32_e64 v2, v2, -v2, vcc
	v_rcp_f32_e32 v47, v3
	v_cvt_pk_bf16_f32 v32, v2, v0
	s_waitcnt lgkmcnt(1)
	v_mul_f32_e64 v0, |v36|, -2.0
	v_mul_f32_e32 v0, 0x3fb8aa3b, v0
	v_pk_add_f32 v[2:3], v[44:45], 1.0 op_sel_hi:[1,0] neg_lo:[1,0] neg_hi:[1,0]
	v_exp_f32_e32 v44, v0
	v_mul_f32_e64 v0, |v37|, -2.0
	v_mul_f32_e32 v0, 0x3fb8aa3b, v0
	v_pk_mul_f32 v[2:3], v[2:3], v[46:47]
	v_exp_f32_e32 v45, v0
	v_cmp_gt_f32_e32 vcc, 0, v35
	s_waitcnt lgkmcnt(0)
	v_cvt_pk_bf16_f32 v40, v40, v41
	v_cvt_pk_bf16_f32 v41, v42, v43
	v_cndmask_b32_e64 v0, v3, -v3, vcc
	v_cmp_gt_f32_e32 vcc, 0, v34
	v_add_f32_e32 v3, 1.0, v44
	v_rcp_f32_e32 v46, v3
	v_cndmask_b32_e64 v2, v2, -v2, vcc
	v_cvt_pk_bf16_f32 v33, v2, v0
	v_mul_f32_e64 v0, |v38|, -2.0
	v_add_f32_e32 v3, 1.0, v45
	v_mul_f32_e32 v0, 0x3fb8aa3b, v0
	v_rcp_f32_e32 v47, v3
	v_pk_add_f32 v[2:3], v[44:45], 1.0 op_sel_hi:[1,0] neg_lo:[1,0] neg_hi:[1,0]
	v_exp_f32_e32 v44, v0
	v_mul_f32_e64 v0, |v39|, -2.0
	v_mul_f32_e32 v0, 0x3fb8aa3b, v0
	v_exp_f32_e32 v45, v0
	v_pk_mul_f32 v[2:3], v[2:3], v[46:47]
	v_cmp_gt_f32_e32 vcc, 0, v37
	s_nop 1
	v_cndmask_b32_e64 v0, v3, -v3, vcc
	v_add_f32_e32 v3, 1.0, v44
	v_rcp_f32_e32 v46, v3
	v_add_f32_e32 v3, 1.0, v45
	v_rcp_f32_e32 v47, v3
	v_cmp_gt_f32_e32 vcc, 0, v36
	s_nop 1
	v_cndmask_b32_e64 v2, v2, -v2, vcc
	v_cvt_pk_bf16_f32 v34, v2, v0
	v_pk_add_f32 v[2:3], v[44:45], 1.0 op_sel_hi:[1,0] neg_lo:[1,0] neg_hi:[1,0]
	v_cmp_gt_f32_e32 vcc, 0, v39
	v_pk_mul_f32 v[2:3], v[2:3], v[46:47]
	s_nop 0
	v_cndmask_b32_e64 v0, v3, -v3, vcc
	v_cmp_gt_f32_e32 vcc, 0, v38
	ds_read_b128 v[36:39], v91
	ds_read_b128 v[44:47], v89 offset:912
	v_cndmask_b32_e64 v2, v2, -v2, vcc
	v_cvt_pk_bf16_f32 v35, v2, v0
	ds_read_b128 v[58:61], v91 offset:5120
	ds_read2st64_b32 v[2:3], v207 offset0:64 offset1:65
	s_waitcnt lgkmcnt(3)
; #define LAS __attribute__((address_space(3)))
; __device__ __forceinline__ unsigned cvt_pk_bf16(float lo, float hi) { const f32x2_t v = {lo, hi}; const bf16x2_t b = __builtin_convertvector(v, bf16x2_t); return __builtin_bit_cast(unsigned, b); }
; __device__ __forceinline__ float bf_lo(unsigned w) { return __uint_as_float(w << 16); }
; __device__ __forceinline__ float bf_hi(unsigned w) { return __uint_as_float(w & 0xffff0000u); }
; __device__ void rwkv_chunk_phase(const Params& p, int l, LAS unsigned char* lds) {
;     ...
;                 const int col = ct * 16 + r16; const float w0c = c_s[col], a0c = c_s[64 + col];
;                 f32x4 lwv, lo;
; #pragma unroll
;                 for (int j = 0; j < 4; ++j) { const int tr_ = rt * 16 + quad * 4 + j; lwv[j] = -__expf(-softplus_(-(cw[j] + w0c)) - 0.5f); y_s[tr_ * 64 + col] = lwv[j]; lg_s[tr_ * 64 + col] = ca[j] + a0c; }
;                 const unsigned h01 = cvt_pk_bf16(lwv[0], lwv[1]), h23 = cvt_pk_bf16(lwv[2], lwv[3]);
;                 lo[0] = lwv[0] - bf_lo(h01); lo[1] = lwv[1] - bf_hi(h01); lo[2] = lwv[2] - bf_lo(h23); lo[3] = lwv[3] - bf_hi(h23);
;                 u32x2 hw; hw.x = h01; hw.y = h23; *(LAS u32x2*)(lwT_hi + col * 40 + rt * 16 + quad * 4) = hw; st_bf4(lwT_lo + col * 40 + rt * 16 + quad * 4, lo); }
;             LBAR();
;             {   const f32x4 wp = *(const LAS f32x4*)(y_s + tok * 64 + j0), ap = *(const LAS f32x4*)(lg_s + tok * 64 + j0);
;                 r4 = *(const LAS f32x4*)(sh_s + tok * 256 + j0); const f32x4 kv4 = *(const LAS f32x4*)(sh_s + tok * 256 + 64 + j0); v4 = *(const LAS f32x4*)(sh_s + tok * 256 + 128 + j0);
;                 float ss = 0.f, bs = 0.f;
; #pragma unroll
;                 for (int j = 0; j < 4; ++j) { kk4[j] = kv4[j] * c_s[128 + j0 + j]; ss += kk4[j] * kk4[j]; }
;                 ss = red16d(ss);
;                 const float rn_ = rsqrtf(ss + 1e-12f);
; #pragma unroll
;                 for (int j = 0; j < 4; ++j) {
;                     const float a = sigmoid_(ap[j]);
;                     lw4[j] = wp[j];
;                     kk4[j] *= rn_; b4[j] = kk4[j] * a;
;                     kd4[j] = kv4[j] * (1.0f + (a - 1.0f) * c_s[192 + j0 + j]);
;                     bs += r4[j] * kd4[j] * c_s[256 + j0 + j];
;                 }
;                 bs = red16d(bs);
;                 if (dir == 0 && cg == 0) BON[(t0 + tokm) * 8 + h] = bs;
	v_mfma_f32_16x16x32_bf16 v[32:35], v[32:35], v[36:39], 0
	s_waitcnt lgkmcnt(2)
	v_cvt_pk_bf16_f32 v42, v44, v45
	v_cvt_pk_bf16_f32 v43, v46, v47
	s_waitcnt lgkmcnt(0)
	s_nop 3
	v_add_f32_e32 v0, v32, v2
	v_mul_f32_e64 v32, |v0|, s97
	v_exp_f32_e32 v32, v32
	v_add_f32_e32 v33, v33, v2
	v_max_f32_e64 v0, -v0, 0
	v_add_f32_e32 v34, v34, v2
	v_add_f32_e32 v32, 1.0, v32
	v_add_f32_e32 v2, v35, v2
	v_mul_f32_e64 v35, |v2|, s97
	v_log_f32_e32 v32, v32
	v_mfma_f32_16x16x32_bf16 v[36:39], v[40:43], v[58:61], 0
	v_exp_f32_e32 v35, v35
	v_max_f32_e64 v2, -v2, 0
	v_mul_f32_e32 v40, 0x3f317217, v32
	v_fma_f32 v40, v32, s48, -v40
	v_fmac_f32_e32 v40, 0x3377d1cf, v32
	v_fmac_f32_e32 v40, 0x3f317217, v32
	v_add_f32_e32 v35, 1.0, v35
	v_add_f32_e32 v37, v37, v3
	v_mov_b32_e32 v32, v40
	v_mul_f32_e64 v40, |v33|, s97
	v_exp_f32_e32 v40, v40
	v_add_f32_e32 v0, v0, v32
	v_sub_f32_e32 v0, -0.5, v0
	v_mul_f32_e32 v0, 0x3fb8aa3b, v0
	v_add_f32_e32 v32, 1.0, v40
	v_cmp_gt_f32_e32 vcc, s33, v32
	v_max_f32_e64 v33, -v33, 0
	v_add_f32_e32 v38, v38, v3
	v_cndmask_b32_e64 v40, 0, 32, vcc
	v_ldexp_f32 v32, v32, v40
	v_log_f32_e32 v40, v32
	v_exp_f32_e32 v32, v0
	v_add_f32_e32 v0, v36, v3
	v_add_f32_e32 v39, v39, v3
	v_mul_f32_e32 v36, 0x3f317217, v40
	v_fma_f32 v36, v40, s48, -v36
	v_fmac_f32_e32 v36, 0x3377d1cf, v40
	v_fmac_f32_e32 v36, 0x3f317217, v40
	v_cmp_lt_f32_e64 s[24:25], |v40|, s49
	s_nop 1
	v_cndmask_b32_e64 v36, v40, v36, s[24:25]
	v_cndmask_b32_e32 v40, 0, v176, vcc
	v_sub_f32_e32 v36, v36, v40
	v_mul_f32_e64 v40, |v34|, s97
	v_exp_f32_e32 v40, v40
	v_add_f32_e32 v33, v33, v36
	v_max_f32_e64 v34, -v34, 0
	v_sub_f32_e32 v33, -0.5, v33
	v_add_f32_e32 v36, 1.0, v40
	v_mul_f32_e32 v33, 0x3fb8aa3b, v33
	v_exp_f32_e32 v33, v33
	v_log_f32_e32 v36, v36
	s_nop 0
	v_mul_f32_e32 v40, 0x3f317217, v36
	v_fma_f32 v40, v36, s48, -v40
	v_fmac_f32_e32 v40, 0x3377d1cf, v36
	v_fmac_f32_e32 v40, 0x3f317217, v36
	v_mov_b32_e32 v36, v40
	v_add_f32_e32 v34, v34, v36
	v_sub_f32_e32 v34, -0.5, v34
	v_log_f32_e32 v35, v35
	v_mul_f32_e32 v34, 0x3fb8aa3b, v34
	v_exp_f32_e32 v34, v34
	v_xor_b32_e32 v40, 0x80000000, v32
	v_mul_f32_e32 v36, 0x3f317217, v35
	v_fma_f32 v36, v35, s48, -v36
	v_fmac_f32_e32 v36, 0x3377d1cf, v35
	v_fmac_f32_e32 v36, 0x3f317217, v35
	v_mov_b32_e32 v35, v36
	v_add_f32_e32 v2, v2, v35
	v_sub_f32_e32 v2, -0.5, v2
	v_mul_f32_e32 v2, 0x3fb8aa3b, v2
	v_exp_f32_e32 v35, v2
	v_pk_add_f32 v[2:3], v[32:33], 0 neg_lo:[1,1] neg_hi:[1,1]
	v_xor_b32_e32 v36, 0x80000000, v33
	v_cvt_pk_bf16_f32 v2, v2, v3
	ds_write2st64_b32 v148, v0, v40 offset0:82 offset1:114
	ds_write2st64_b32 v150, v37, v36 offset0:82 offset1:114
	v_lshlrev_b32_e32 v36, 16, v2
	v_and_b32_e32 v37, 0xffff0000, v2
	v_pk_add_f32 v[32:33], v[32:33], v[36:37] neg_lo:[1,1] neg_hi:[1,1]
	v_pk_add_f32 v[36:37], v[34:35], 0 neg_lo:[1,1] neg_hi:[1,1]
	v_xor_b32_e32 v3, 0x80000000, v34
	v_xor_b32_e32 v0, 0x80000000, v35
	ds_write2st64_b32 v152, v38, v3 offset0:82 offset1:114
	ds_write2st64_b32 v154, v39, v0 offset0:82 offset1:114
	v_cvt_pk_bf16_f32 v3, v36, v37
	v_lshlrev_b32_e32 v36, 16, v3
	v_and_b32_e32 v37, 0xffff0000, v3
	v_pk_add_f32 v[34:35], v[34:35], v[36:37] neg_lo:[1,1] neg_hi:[1,1]
	ds_write_b64 v92, v[2:3]
	v_cvt_pk_bf16_f32 v2, v32, v33
	v_cvt_pk_bf16_f32 v3, v34, v35
	ds_write_b64 v93, v[2:3]
	s_waitcnt lgkmcnt(0)
	s_barrier
	ds_read_b128 v[36:39], v94 offset:29184
	ds_read_b128 v[32:35], v94 offset:20992
	ds_read_b128 v[44:47], v96 offset:17408
	ds_read_b128 v[218:221], v96 offset:17152
	ds_read_b128 v[40:43], v95
	ds_read_b128 v[222:225], v95 offset:256
	s_and_b64 s[24:25], s[4:5], exec
	s_cselect_b32 s24, s62, s63
	s_lshl_b32 s24, s24, 5
	s_waitcnt lgkmcnt(4)
	v_mul_f32_e32 v0, 0xbfb8aa3b, v32
	v_exp_f32_e32 v0, v0
	v_mul_f32_e32 v2, 0xbfb8aa3b, v33
	v_exp_f32_e32 v2, v2
	s_or_b32 s24, s60, s24
	v_add_f32_e32 v0, 1.0, v0
	v_rcp_f32_e32 v64, v0
	v_add_f32_e32 v0, 1.0, v2
	v_rcp_f32_e32 v65, v0
	s_mov_b32 s25, s61
	v_lshl_add_u64 v[58:59], s[24:25], 0, v[52:53]
	v_pk_add_f32 v[2:3], v[64:65], -1.0 op_sel_hi:[1,0]
	s_waitcnt lgkmcnt(2)
	v_pk_fma_f32 v[2:3], v[2:3], v[218:219], 1.0 op_sel_hi:[1,1,0]
	s_waitcnt lgkmcnt(0)
	v_pk_mul_f32 v[62:63], v[222:223], v[2:3]
	v_mul_f32_e32 v3, 0xbfb8aa3b, v35
	v_mul_f32_e32 v0, v40, v62
	v_fma_f32 v0, v44, v0, 0
	v_mul_f32_e32 v2, v41, v63
	v_fmac_f32_e32 v0, v45, v2
	v_mul_f32_e32 v2, 0xbfb8aa3b, v34
	ds_read_b128 v[32:35], v95 offset:512
	ds_read_b128 v[226:229], v96 offset:16896
	v_exp_f32_e32 v2, v2
	v_exp_f32_e32 v3, v3
	v_add_f32_e32 v2, 1.0, v2
	s_waitcnt lgkmcnt(0)
	v_pk_mul_f32 v[70:71], v[222:223], v[226:227]
	v_rcp_f32_e32 v66, v2
	v_add_f32_e32 v2, 1.0, v3
	v_pk_mul_f32 v[68:69], v[224:225], v[228:229]
	v_pk_mul_f32 v[44:45], v[70:71], v[70:71]
	v_rcp_f32_e32 v67, v2
	v_pk_mul_f32 v[2:3], v[68:69], v[68:69]
	v_add_f32_e32 v44, v44, v45
	v_add_f32_e32 v2, v44, v2
	v_add_f32_e32 v2, v2, v3
	s_nop 1
	v_add_f32_dpp v2, v2, v2 quad_perm:[1,0,3,2] row_mask:0xf bank_mask:0xf bound_ctrl:1
	s_nop 1
	v_add_f32_dpp v2, v2, v2 quad_perm:[2,3,0,1] row_mask:0xf bank_mask:0xf bound_ctrl:1
	s_nop 1
	v_add_f32_dpp v51, v2, v2 row_half_mirror row_mask:0xf bank_mask:0xf bound_ctrl:1
	v_pk_add_f32 v[2:3], v[66:67], -1.0 op_sel_hi:[1,0]
	s_nop 0
	v_pk_fma_f32 v[2:3], v[2:3], v[220:221], 1.0 op_sel_hi:[1,1,0]
	v_mov_b32_dpp v218, v51 row_mirror row_mask:0xf bank_mask:0xf bound_ctrl:1
	v_pk_mul_f32 v[60:61], v[224:225], v[2:3]
	s_nop 0
	v_mul_f32_e32 v2, v42, v60
	v_fmac_f32_e32 v0, v46, v2
	v_mul_f32_e32 v2, v43, v61
	v_fmac_f32_e32 v0, v47, v2
	s_nop 1
	v_add_f32_dpp v0, v0, v0 quad_perm:[1,0,3,2] row_mask:0xf bank_mask:0xf bound_ctrl:1
	s_nop 1
	v_add_f32_dpp v0, v0, v0 quad_perm:[2,3,0,1] row_mask:0xf bank_mask:0xf bound_ctrl:1
	s_nop 1
	v_add_f32_dpp v0, v0, v0 row_half_mirror row_mask:0xf bank_mask:0xf bound_ctrl:1
	s_nop 1
	v_mov_b32_dpp v2, v0 row_mirror row_mask:0xf bank_mask:0xf bound_ctrl:1
	s_and_saveexec_b64 s[24:25], s[6:7]
	s_cbranch_execz .LBB0_323
	v_add_f32_e32 v0, v0, v2
	v_lshlrev_b64 v[2:3], 5, v[58:59]
	v_lshl_add_u64 v[2:3], s[40:41], 0, v[2:3]
	global_store_dword v[2:3], v0, off

; #define LAS __attribute__((address_space(3)))
; __device__ __forceinline__ unsigned cvt_pk_bf16(float lo, float hi) { const f32x2_t v = {lo, hi}; const bf16x2_t b = __builtin_convertvector(v, bf16x2_t); return __builtin_bit_cast(unsigned, b); }
; __device__ __forceinline__ float bf_lo(unsigned w) { return __uint_as_float(w << 16); }
; __device__ __forceinline__ float bf_hi(unsigned w) { return __uint_as_float(w & 0xffff0000u); }
; __device__ __forceinline__ float softplus_(float x) { return fmaxf(x, 0.f) + __logf(1.0f + __expf(-fabsf(x))); }
; #define LBAR() do { asm volatile("s_waitcnt lgkmcnt(0)" ::: "memory"); __builtin_amdgcn_s_barrier(); asm volatile("" ::: "memory"); } while (0)
; __device__ void gla_chunk_phase(const Params& p, int l, LAS unsigned char* lds) {
;     ...
;             for (int i = 0; i < 2; ++i) { const int id = wid + 8 * i, rt = id >> 2, ct = id & 3; const f32x4 z4 = {0.f, 0.f, 0.f, 0.f};
;                 const f32x4 z = mm_nt<1>(dnA, 40, rt * 16, upT, 40, ct * 16, r16, quad, z4);
;                 const int col = ct * 16 + r16; const float bz = bias_s[col];
;                 f32x4 la, lo;
; #pragma unroll
;                 for (int j = 0; j < 4; ++j) la[j] = -softplus_(-(z[j] + bz)) * (1.0f / 16.0f);
;                 const unsigned h01 = cvt_pk_bf16(la[0], la[1]), h23 = cvt_pk_bf16(la[2], la[3]);
;                 lo[0] = la[0] - bf_lo(h01); lo[1] = la[1] - bf_hi(h01); lo[2] = la[2] - bf_lo(h23); lo[3] = la[3] - bf_hi(h23);
;                 u32x2 hw; hw.x = h01; hw.y = h23; *(LAS u32x2*)(laT_hi + col * 72 + rt * 16 + quad * 4) = hw;
;                 st_bf4(laT_lo + col * 72 + rt * 16 + quad * 4, lo); }
;             LBAR();
; #pragma unroll
;             for (int i = 0; i < 2; ++i) { const int id = wid + 8 * i, rt = id >> 2, ct = id & 3; const f32x4 z4 = {0.f, 0.f, 0.f, 0.f};
;                 f32x4 acc = mm_nt<2>(Lm, 72, rt * 16, laT_hi, 72, ct * 16, r16, quad, z4);
;                 acc = mm_nt<2>(Lm, 72, rt * 16, laT_lo, 72, ct * 16, r16, quad, acc);
;                 const int col = ct * 16 + r16;
; #pragma unroll
;                 for (int j = 0; j < 4; ++j) b_s[(rt * 16 + quad * 4 + j) * 64 + col] = acc[j];
;                 if (rt == 3 && quad == 3) { tot_s[col] = acc[3]; dk_s[col] = __expf(acc[3]); } }
.LBB0_443:
	s_waitcnt lgkmcnt(0)
	s_barrier
	v_add_u32_e32 v42, v69, v83
	ds_read_b128 v[42:45], v42
	ds_read_b128 v[116:119], v70
	ds_read_b32 v53, v71
	s_waitcnt lgkmcnt(0)
	v_mfma_f32_16x16x32_bf16 v[42:45], v[42:45], v[116:119], 0
	s_nop 7
	v_add_f32_e32 v62, v53, v42
	v_max_f32_e64 v42, -v62, 0
	v_mul_f32_e64 v62, |v62|, s97
	v_exp_f32_e32 v62, v62
	s_nop 0
	v_add_f32_e32 v62, 1.0, v62
	v_log_f32_e32 v62, v62
	s_nop 0
	v_mul_f32_e32 v63, 0x3f317217, v62
	v_fma_f32 v63, v62, s48, -v63
	v_fmac_f32_e32 v63, 0x3377d1cf, v62
	v_fmac_f32_e32 v63, 0x3f317217, v62
	v_mov_b32_e32 v62, v63
	v_add_f32_e32 v63, v53, v43
	v_max_f32_e64 v43, -v63, 0
	v_mul_f32_e64 v63, |v63|, s97
	v_exp_f32_e32 v63, v63
	s_nop 0
	v_add_f32_e32 v63, 1.0, v63
	v_log_f32_e32 v63, v63
	s_nop 0
	v_mul_f32_e32 v115, 0x3f317217, v63
	v_fma_f32 v115, v63, s48, -v115
	v_fmac_f32_e32 v115, 0x3377d1cf, v63
	v_fmac_f32_e32 v115, 0x3f317217, v63
	v_mov_b32_e32 v63, v115
	v_add_f32_e32 v115, v53, v44
	v_max_f32_e64 v44, -v115, 0
	v_mul_f32_e64 v115, |v115|, s97
	v_exp_f32_e32 v115, v115
	v_add_f32_e32 v53, v53, v45
	v_max_f32_e64 v45, -v53, 0
	v_mul_f32_e64 v53, |v53|, s97
	v_add_f32_e32 v115, 1.0, v115
	v_exp_f32_e32 v53, v53
	v_pk_add_f32 v[42:43], v[42:43], v[62:63]
	v_log_f32_e32 v115, v115
	v_add_f32_e32 v53, 1.0, v53
	v_pk_mul_f32 v[62:63], v[42:43], s[96:97] op_sel_hi:[1,0]
	v_mul_f32_e32 v116, 0x3f317217, v115
	v_fma_f32 v116, v115, s48, -v116
	v_fmac_f32_e32 v116, 0x3377d1cf, v115
	v_fmac_f32_e32 v116, 0x3f317217, v115
	v_cvt_pk_bf16_f32 v62, v62, v63
	v_lshlrev_b32_e32 v118, 16, v62
	v_mov_b32_e32 v115, v116
	v_mov_b32_e32 v116, v115
	v_and_b32_e32 v119, 0xffff0000, v62
	v_log_f32_e32 v53, v53
	v_pk_fma_f32 v[42:43], v[42:43], s[96:97], v[118:119] op_sel_hi:[1,0,1] neg_lo:[0,0,1] neg_hi:[0,0,1]
	v_mul_f32_e32 v115, 0x3f317217, v53
	v_fma_f32 v115, v53, s48, -v115
	v_fmac_f32_e32 v115, 0x3377d1cf, v53
	v_fmac_f32_e32 v115, 0x3f317217, v53
	v_cvt_pk_bf16_f32 v42, v42, v43
	s_nop 0
	v_mov_b32_e32 v53, v115
	v_mov_b32_e32 v117, v53
	v_pk_add_f32 v[44:45], v[44:45], v[116:117]
	s_nop 0
	v_pk_mul_f32 v[116:117], v[44:45], s[96:97] op_sel_hi:[1,0]
	s_nop 0
	v_cvt_pk_bf16_f32 v63, v116, v117
	v_lshlrev_b32_e32 v116, 16, v63
	v_and_b32_e32 v117, 0xffff0000, v63
	v_pk_fma_f32 v[44:45], v[44:45], s[96:97], v[116:117] op_sel_hi:[1,0,1] neg_lo:[0,0,1] neg_hi:[0,0,1]
	ds_write_b64 v84, v[62:63]
	v_cvt_pk_bf16_f32 v43, v44, v45
	ds_write_b64 v85, v[42:43]
	ds_read_b128 v[42:45], v105
	ds_read_b128 v[116:119], v70
	ds_read_b32 v53, v71
	s_waitcnt lgkmcnt(0)
	v_mfma_f32_16x16x32_bf16 v[42:45], v[42:45], v[116:119], 0
	s_nop 7
	v_add_f32_e32 v62, v53, v42
	v_max_f32_e64 v42, -v62, 0
	v_mul_f32_e64 v62, |v62|, s97
	v_exp_f32_e32 v62, v62
	s_nop 0
	v_add_f32_e32 v62, 1.0, v62
	v_log_f32_e32 v62, v62
	s_nop 0
	v_mul_f32_e32 v63, 0x3f317217, v62
	v_fma_f32 v63, v62, s48, -v63
	v_fmac_f32_e32 v63, 0x3377d1cf, v62
	v_fmac_f32_e32 v63, 0x3f317217, v62
	v_mov_b32_e32 v62, v63
	v_add_f32_e32 v63, v53, v43
	v_max_f32_e64 v43, -v63, 0
	v_mul_f32_e64 v63, |v63|, s97
	v_exp_f32_e32 v63, v63
	s_nop 0
	v_add_f32_e32 v63, 1.0, v63
	v_log_f32_e32 v63, v63
	s_nop 0
	v_mul_f32_e32 v115, 0x3f317217, v63
	v_fma_f32 v115, v63, s48, -v115
	v_fmac_f32_e32 v115, 0x3377d1cf, v63
	v_fmac_f32_e32 v115, 0x3f317217, v63
	v_mov_b32_e32 v63, v115
	v_add_f32_e32 v115, v53, v44
	v_max_f32_e64 v44, -v115, 0
	v_mul_f32_e64 v115, |v115|, s97
	v_exp_f32_e32 v115, v115
	v_add_f32_e32 v53, v53, v45
	v_max_f32_e64 v45, -v53, 0
	v_mul_f32_e64 v53, |v53|, s97
	v_add_f32_e32 v115, 1.0, v115
	v_exp_f32_e32 v53, v53
	v_pk_add_f32 v[42:43], v[42:43], v[62:63]
	v_log_f32_e32 v115, v115
	v_add_f32_e32 v53, 1.0, v53
	v_pk_mul_f32 v[62:63], v[42:43], s[96:97] op_sel_hi:[1,0]
	v_mul_f32_e32 v116, 0x3f317217, v115
	v_fma_f32 v116, v115, s48, -v116
	v_fmac_f32_e32 v116, 0x3377d1cf, v115
	v_fmac_f32_e32 v116, 0x3f317217, v115
	v_cvt_pk_bf16_f32 v62, v62, v63
	v_lshlrev_b32_e32 v118, 16, v62
	v_mov_b32_e32 v115, v116
	v_mov_b32_e32 v116, v115
	v_and_b32_e32 v119, 0xffff0000, v62
	v_log_f32_e32 v53, v53
	v_pk_fma_f32 v[42:43], v[42:43], s[96:97], v[118:119] op_sel_hi:[1,0,1] neg_lo:[0,0,1] neg_hi:[0,0,1]
	v_mul_f32_e32 v115, 0x3f317217, v53
	v_fma_f32 v115, v53, s48, -v115
	v_fmac_f32_e32 v115, 0x3377d1cf, v53
	v_fmac_f32_e32 v115, 0x3f317217, v53
	v_cvt_pk_bf16_f32 v42, v42, v43
	s_nop 0
	v_mov_b32_e32 v53, v115
	v_mov_b32_e32 v117, v53
	v_pk_add_f32 v[44:45], v[44:45], v[116:117]
	v_add_u32_e32 v53, v72, v68
	v_pk_mul_f32 v[116:117], v[44:45], s[96:97] op_sel_hi:[1,0]
	s_nop 0
	v_cvt_pk_bf16_f32 v63, v116, v117
	v_lshlrev_b32_e32 v116, 16, v63
	v_and_b32_e32 v117, 0xffff0000, v63
	v_pk_fma_f32 v[44:45], v[44:45], s[96:97], v[116:117] op_sel_hi:[1,0,1] neg_lo:[0,0,1] neg_hi:[0,0,1]
	ds_write_b64 v84, v[62:63] offset:64
	v_cvt_pk_bf16_f32 v43, v44, v45
	ds_write_b64 v85, v[42:43] offset:64
	s_waitcnt lgkmcnt(0)
	s_barrier
	ds_read_b128 v[42:45], v106
	ds_read_b128 v[116:119], v53
	ds_read_b128 v[120:123], v106 offset:64
	ds_read_b128 v[124:127], v53 offset:64
	s_waitcnt lgkmcnt(0)
	v_mfma_f32_16x16x32_bf16 v[116:119], v[42:45], v[116:119], 0
	v_add_u32_e32 v62, v73, v68
	v_mfma_f32_16x16x32_bf16 v[116:119], v[120:123], v[124:127], v[116:119]
	ds_read_b128 v[124:127], v62
	s_waitcnt lgkmcnt(0)
	v_mfma_f32_16x16x32_bf16 v[42:45], v[42:45], v[124:127], v[116:119]
	s_nop 4
	ds_read_b128 v[116:119], v62 offset:64
	s_waitcnt lgkmcnt(0)
	v_mfma_f32_16x16x32_bf16 v[42:45], v[120:123], v[116:119], v[42:45]
	s_nop 7
	ds_write2st64_b32 v107, v42, v43 offset1:1
	ds_write2st64_b32 v107, v44, v45 offset0:2 offset1:3
	s_and_saveexec_b64 s[20:21], s[88:89]
	s_cbranch_execz .LBB0_445
	v_mul_f32_e32 v42, 0x3fb8aa3b, v45
	v_exp_f32_e32 v42, v42
	ds_write_b32 v75, v45
	ds_write_b32 v74, v42
